# lean converter (phase 1 + ab_w_in in phase 0, gridDim==256 guarded), GEMM loops: no setprio flips, loader VALU removed
# speedup vs baseline: 1.0086x; 1.0086x over previous
; #define LAS __attribute__((address_space(3)))
; template <class F, bool NT = true> __device__ __forceinline__ void tr_run(F item, int first, int step, int n, LAS float* scr, int lane) {
;     if (first >= n) return;
;     TrDesc da = item(first), db = da, dc = da; f32x4 va[8], vb[8], vc[8];
;     tr_load<NT>(da, va, lane);
;     if (first + step < n) { db = item(first + step); tr_load<NT>(db, vb, lane); }
;     for (int it = first; it < n; it += 3 * step) {
; __device__ __forceinline__ void phase_p0(const Params& p, LAS unsigned char* lds, int gw, int ngw, int wave, int lane) {
;     unsigned char* ws = p.ws;
;     LAS float* scr = (LAS float*)(lds + wave * 8704);
;     { P0Item pi{&p, 0}; tr_run<P0Item, false>(pi, gw, ngw, P0A_ITEMS, scr, lane); }
.LBB0_11:
	s_or_b64 exec, exec, s[2:3]
	v_readlane_b32 s2, v240, 1
	s_lshr_b32 s6, s2, 6
	v_readlane_b32 s2, v240, 0
	s_mov_b32 s4, s6
	s_lshl_b32 s2, s2, 3
	v_writelane_b32 v240, s4, 25
	s_lshl_b32 s36, s92, 3
	s_add_i32 s2, s6, s2
	v_writelane_b32 v240, s5, 26
	v_writelane_b32 v240, s2, 27
	s_cmp_lt_i32 s40, 1
	v_and_b32_e32 v164, 63, v0
	v_writelane_b32 v240, s3, 28
	s_cselect_b64 s[2:3], -1, 0
	s_cmp_gt_i32 s41, 0
	s_cselect_b64 s[4:5], -1, 0
	s_and_b64 s[2:3], s[2:3], s[4:5]
	s_andn2_b64 vcc, exec, s[2:3]
	s_cbranch_vccnz .LBB0_120
	s_cmpk_eq_i32 s92, 0x100
	s_cbranch_scc1 .LBB0_58
	v_readlane_b32 s2, v240, 27
	s_cmpk_gt_i32 s2, 0x5fff
	v_readlane_b32 s3, v240, 28
	s_cbranch_scc1 .LBB0_58
	v_readlane_b32 s16, v240, 27
	s_add_u32 s26, s58, 0x100000
	s_mul_hi_i32 s2, s16, 0x2aaaaaab
	s_addc_u32 s27, s59, 0
	s_lshr_b32 s3, s2, 31
	s_ashr_i32 s2, s2, 5
	s_load_dwordx16 s[60:75], s[0:1], 0x0
	s_add_i32 s12, s2, s3
	s_lshl_b32 s8, s12, 6
	s_ashr_i32 s9, s8, 31
	s_lshl_b64 s[2:3], s[8:9], 2
	s_waitcnt lgkmcnt(0)
	s_add_u32 s6, s62, s2
	s_addc_u32 s7, s63, s3
	s_cmp_eq_u64 s[62:63], 0
	s_cselect_b64 s[2:3], -1, 0
	s_and_b64 s[4:5], s[2:3], exec
	s_mul_i32 s4, s12, 0xc0
	s_cselect_b32 s7, 0, s7
	s_cselect_b32 s6, 0, s6
	s_sub_i32 s4, s16, s4
	s_lshl_b32 s10, s4, 5
	s_ashr_i32 s11, s10, 31
	s_lshl_b64 s[4:5], s[10:11], 13
	s_add_u32 s13, s26, s4
	s_addc_u32 s14, s27, s5
	s_lshl_b64 s[4:5], s[8:9], 1
	s_add_u32 s4, s13, s4
	s_addc_u32 s5, s14, s5
	s_mul_i32 s12, s12, 0x302000
	s_mul_hi_i32 s8, s8, 0xc080
	s_add_u32 s12, s72, s12
	s_addc_u32 s13, s73, s8
	s_lshl_b64 s[8:9], s[10:11], 2
	s_add_u32 s8, s12, s8
	s_addc_u32 s9, s13, s9
	s_cmpk_lt_i32 s16, 0x3000
	s_mov_b32 s10, 0xc080
	v_readlane_b32 s17, v240, 28
	s_cbranch_scc1 .LBB0_15
	s_add_i32 s4, s16, 0xffffd000
	s_and_b32 s5, s4, 0xffff
	s_mul_i32 s5, s5, 0xaaab
	s_lshr_b32 s6, s5, 23
	s_mul_i32 s5, s6, 0xc0
	s_sub_i32 s4, s4, s5
	s_and_b32 s5, s4, 0xffff
	s_mul_i32 s7, s6, 0x302000
	s_add_u32 s7, s72, s7
	s_addc_u32 s8, s73, 0
	s_lshl_b32 s5, s5, 7
	s_add_u32 s5, s7, s5
	s_addc_u32 s7, s8, 0
	s_add_u32 s8, s5, 0x6040
	s_addc_u32 s9, s7, 0
	s_lshl_b32 s4, s4, 18
	s_add_u32 s4, s26, s4
	s_addc_u32 s5, s27, 0
	s_lshl_b32 s7, s6, 7
	s_add_u32 s4, s4, s7
	s_addc_u32 s5, s5, 0
	s_add_u32 s4, s4, 0x3000000
	s_addc_u32 s5, s5, 0
	s_lshl_b32 s6, s6, 8
	s_add_u32 s11, s62, s6
	s_addc_u32 s12, s63, 0
	s_and_b64 s[6:7], s[2:3], exec
	s_cselect_b32 s7, 0, s12
	s_cselect_b32 s6, 0, s11

; #define LAS __attribute__((address_space(3)))
; __device__ __forceinline__ bf16_t f2bf(float f) { return (bf16_t)(cvt_pk_bf16(f, 0.f) & 0xffffu); }
; #define SEAM(k) do { if ((k) + 1 < hi) xcd_barrier(bar); } while (0)
; #define SEAM(k) do { if ((k) + 1 < hi) xcd_barrier(bar); } while (0)
; __device__ __forceinline__ void phase_p0(const Params& p, LAS unsigned char* lds, int gw, int ngw, int wave, int lane) {
;     unsigned char* ws = p.ws;
;     LAS float* scr = (LAS float*)(lds + wave * 8704);
;     { P0Item pi{&p, 0}; tr_run<P0Item, false>(pi, gw, ngw, P0A_ITEMS, scr, lane); }
;     { bf16_t* WS_ = (bf16_t*)(ws + WS_WSMALL);
;       for (int i = gw * 64 + lane; i < 32 * DM; i += ngw * 64) { const int c = i & 31, k = i >> 5; const int sc = c < 16 ? 6144 + c : 12304 + (c - 16);
;           WS_[(size_t)c * DM + k] = f2bf(p.ab_w_in[(size_t)k * AB_IN + sc] * p.norm_mix[k]); } }
;     { unsigned long long* ssq0 = (unsigned long long*)(ws + WS_CTL + SSQ0_BYTE_OFF); bf16_t* U = (bf16_t*)(ws + WS_U);
;       for (int m = gw; m < MTOK; m += ngw) x_row_bf16(p.x + (size_t)m * DM, U + (size_t)m * DM, ssq0 + m, lane); }
; }
; __global__ void __launch_bounds__(NTHR, 2) hybrid_fwd(Args args) {
;     ...
;     if (IN(0)) { for (int rep = 0; rep < REP_P0; ++rep) { phase_p0(p, lds, gw, ngw, wave, lane); __syncthreads(); } SEAM(0); }
.LBB0_66:
	s_cmpk_lg_i32 s92, 0x100
	s_cbranch_scc1 .Lpz_resume
